# v29 + staggered phase start (XCD groups offset by ~8us steps) in the six residual-epilogue GEMM phases (P3, P13, P16 both layers) so epilogue HBM bursts of different XCD groups do not coincide
# speedup vs baseline: 1.0012x; 1.0006x over previous
.LBB0_262:
	v_readlane_b32 s2, v243, 51
	s_cmp_lt_i32 s2, 4
	v_readlane_b32 s3, v243, 52
	s_cselect_b64 s[52:53], -1, 0
	s_add_u32 s2, s50, 0x200000
	s_addc_u32 s3, s51, 0
	v_writelane_b32 v242, s2, 19
	s_nop 1
	v_writelane_b32 v242, s3, 20
	s_add_u32 s2, s50, 0x2e100000
	s_addc_u32 s3, s51, 0
	s_and_b64 s[0:1], s[52:53], s[0:1]
	v_writelane_b32 v242, s2, 21
	s_andn2_b64 vcc, exec, s[0:1]
	s_nop 0
	v_writelane_b32 v242, s3, 22
	s_cbranch_vccnz .LBB0_308
	v_readlane_b32 s98, v243, 0
	s_lshr_b32 s98, s98, 0
	s_and_b32 s98, s98, 3
	s_mul_i32 s98, s98, 2
.Ldly_ph3_loop:
	s_cmp_eq_u32 s98, 0
	s_cbranch_scc1 .Ldly_ph3_done
	s_sleep 127
	s_sub_u32 s98, s98, 1
	s_branch .Ldly_ph3_loop
.Ldly_ph3_done:
	v_readlane_b32 s4, v243, 53
	s_abs_i32 s0, s4
	v_cvt_f32_u32_e32 v1, s0
	v_readlane_b32 s6, v243, 0
	s_sub_i32 s1, s4, s6
	s_add_i32 s2, s1, 0x3ff
	v_rcp_iflag_f32_e32 v1, v1
	s_sub_i32 s1, 0xfffffc01, s1
	s_xor_b32 s4, s2, s4
	s_sub_i32 s3, 0, s0
	v_mul_f32_e32 v1, 0x4f7ffffe, v1
	v_cvt_u32_f32_e32 v1, v1
	s_max_i32 s1, s2, s1
	s_ashr_i32 s2, s4, 31
	v_readfirstlane_b32 s4, v1
	s_mul_i32 s3, s3, s4
	s_mul_hi_u32 s3, s4, s3
	s_add_i32 s4, s4, s3
	s_mul_hi_u32 s3, s1, s4
	s_mul_i32 s4, s3, s0
	s_sub_i32 s1, s1, s4
	s_add_i32 s5, s3, 1
	s_sub_i32 s4, s1, s0
	s_cmp_ge_u32 s1, s0
	s_cselect_b32 s3, s5, s3
	s_cselect_b32 s1, s4, s1
	s_add_i32 s4, s3, 1
	s_cmp_ge_u32 s1, s0
	s_cselect_b32 s0, s4, s3
	s_xor_b32 s0, s0, s2
	s_sub_i32 s20, s0, s2
	s_cmp_lt_i32 s20, 1
	v_readfirstlane_b32 s4, v0
	s_cbranch_scc1 .LBB0_267
	s_mov_b64 s[0:1], 0
	s_cmpk_gt_i32 s6, 0x3ff
	s_mov_b64 s[2:3], 0
	s_cbranch_scc1 .LBB0_268
	v_readlane_b32 s3, v243, 0
	s_ashr_i32 s2, s3, 31
	s_lshr_b32 s2, s2, 29
	s_add_i32 s5, s3, s2
	s_and_b32 s2, s5, -8
	s_sub_i32 s6, s3, s2
	s_cmp_gt_i32 s6, -1
	s_cbranch_scc0 .LBB0_272
	s_lshl_b32 s7, s6, 7
	s_cbranch_execz .LBB0_273
	s_branch .LBB0_274

.LBB0_1157:
	v_readlane_b32 s2, v243, 51
	s_cmp_lt_i32 s2, 14
	s_cselect_b64 s[4:5], -1, 0
	s_and_b64 s[0:1], s[4:5], s[0:1]
	s_andn2_b64 vcc, exec, s[0:1]
	v_readlane_b32 s3, v243, 52
	s_cbranch_vccnz .LBB0_1174
	v_readlane_b32 s98, v243, 0
	s_lshr_b32 s98, s98, 0
	s_and_b32 s98, s98, 3
	s_mul_i32 s98, s98, 2

.Ldly_ph12_done:
	v_readlane_b32 s0, v243, 0
	s_cmpk_gt_i32 s0, 0x40f
	v_readfirstlane_b32 s3, v0
	s_cbranch_scc1 .LBB0_1174
	v_lshlrev_b32_e32 v2, 4, v0
	s_add_u32 s20, s90, 0xcd00000
	v_or_b32_e32 v10, 0x2000, v2
	v_readlane_b32 s2, v243, 0
	s_addc_u32 s24, s91, 0
	v_lshrrev_b32_e32 v3, 7, v10
	v_bfe_u32 v13, v0, 2, 4
	s_movk_i32 s0, 0x70
	s_ashr_i32 s26, s2, 31
	v_and_or_b32 v3, v3, s0, v13
	s_lshr_b32 s0, s26, 29
	s_add_i32 s0, s2, s0
	s_lshr_b32 s8, s3, 6
	s_ashr_i32 s1, s0, 3
	s_and_b32 s0, s0, -8
	s_lshr_b32 s10, s3, 8
	s_lshl_b32 s25, s8, 10
	s_sub_i32 s0, s2, s0
	s_cmp_lt_i32 s0, 0
	s_movk_i32 s27, 0x83
	s_cselect_b32 s2, s27, 0x82
	s_mul_i32 s0, s2, s0
	s_add_i32 s0, s0, s1
	s_ashr_i32 s1, s0, 31
	s_lshr_b32 s1, s1, 26
	s_add_i32 s1, s0, s1
	s_ashr_i32 s1, s1, 6
	s_lshl_b32 s6, s1, 3
	s_sub_i32 s2, 0x82, s6
	s_lshl_b32 s1, s1, 6
	s_min_u32 s7, s2, 8
	s_sub_i32 s9, s0, s1
	v_and_b32_e32 v4, 32, v0
	s_sext_i32_i8 s0, s9
	v_cvt_f32_ubyte0_e32 v5, s7
	v_bitop3_b32 v11, v2, v4, 48 bitop3:0x6c
	v_and_b32_e32 v12, 64, v0
	v_cvt_f32_i32_e32 v4, s0
	v_rcp_iflag_f32_e32 v6, v5
	v_or_b32_e32 v2, v11, v12
	v_lshl_or_b32 v142, v3, 12, v2
	v_lshrrev_b32_e32 v3, 3, v0
	v_and_or_b32 v3, v3, 48, v13
	v_lshl_or_b32 v144, v3, 12, v2
	v_mul_f32_e32 v2, v4, v6
	v_trunc_f32_e32 v2, v2
	v_fma_f32 v3, -v2, v5, v4
	v_cvt_i32_f32_e32 v2, v2
	s_ashr_i32 s0, s0, 30
	s_or_b32 s2, s0, 1
	v_cmp_ge_f32_e64 s[0:1], |v3|, v5
	s_and_b64 s[0:1], s[0:1], exec
	s_cselect_b32 s0, s2, 0
	v_readfirstlane_b32 s1, v2
	s_add_i32 s2, s1, s0
	s_mul_i32 s0, s2, s7
	s_sub_i32 s0, s9, s0
	s_sext_i32_i8 s0, s0
	s_add_i32 s86, s6, s0
	s_ashr_i32 s87, s86, 31
	s_bfe_i64 s[0:1], s[2:3], 0x80000
	s_lshl_b64 s[6:7], s[86:87], 20
	s_lshl_b64 s[0:1], s[0:1], 20
	s_add_u32 s0, s20, s0
	s_addc_u32 s1, s24, s1
	s_add_i32 s30, s25, 0
	s_add_i32 m0, s30, 0x10000
	v_mov_b32_e32 v145, 0
	global_load_lds_dwordx4 v144, s[0:1]
	s_add_i32 m0, s30, 0x12000
	s_add_u32 s12, s0, 0x80000
	global_load_lds_dwordx4 v142, s[0:1]
	s_addc_u32 s13, s1, 0
	s_add_i32 m0, s30, 0x14000
	v_mov_b32_e32 v143, v145
	global_load_lds_dwordx4 v144, s[12:13]
	s_add_i32 m0, s30, 0x16000
	s_mov_b32 s35, 0
	global_load_lds_dwordx4 v142, s[12:13]
	v_readlane_b32 s12, v242, 15
	v_readlane_b32 s13, v242, 16
	s_add_u32 s22, s12, s6
	s_addc_u32 s23, s13, s7
	s_add_i32 s31, s30, 0x2000
	s_mov_b32 m0, s30
	s_add_u32 s6, s22, 0x80000
	global_load_lds_dwordx4 v144, s[22:23]
	s_mov_b32 m0, s31
	s_addc_u32 s7, s23, 0
	s_add_i32 s33, s30, 0x4000
	global_load_lds_dwordx4 v142, s[22:23]
	s_mov_b32 m0, s33
	s_add_i32 s34, s30, 0x6000
	global_load_lds_dwordx4 v144, s[6:7]
	s_mov_b32 m0, s34
	s_cmp_eq_u32 s10, 1
	global_load_lds_dwordx4 v142, s[6:7]
	v_lshl_add_u64 v[8:9], s[0:1], 0, v[144:145]
	v_lshl_add_u64 v[6:7], s[0:1], 0, v[142:143]
	v_lshl_add_u64 v[2:3], s[22:23], 0, v[144:145]
	s_cselect_b64 s[6:7], -1, 0
	s_cmp_lg_u32 s10, 1
	v_lshl_add_u64 v[4:5], s[22:23], 0, v[142:143]
	s_cbranch_scc1 .LBB0_1161
	s_barrier

.LBB0_1357:
	v_readlane_b32 s2, v243, 51
	s_cmp_lt_i32 s2, 17
	s_cselect_b64 s[52:53], -1, 0
	s_and_b64 s[0:1], s[52:53], s[0:1]
	s_andn2_b64 vcc, exec, s[0:1]
	v_readlane_b32 s3, v243, 52
	s_cbranch_vccnz .LBB0_1403
	v_readlane_b32 s98, v243, 0
	s_lshr_b32 s98, s98, 0
	s_and_b32 s98, s98, 3
	s_mul_i32 s98, s98, 2

.Ldly_ph15_done:
	v_readlane_b32 s4, v243, 53
	s_abs_i32 s0, s4
	v_cvt_f32_u32_e32 v2, s0
	v_readlane_b32 s6, v243, 0
	s_sub_i32 s1, s4, s6
	s_add_i32 s2, s1, 0x3ff
	v_rcp_iflag_f32_e32 v2, v2
	s_sub_i32 s1, 0xfffffc01, s1
	s_xor_b32 s4, s2, s4
	s_sub_i32 s3, 0, s0
	v_mul_f32_e32 v2, 0x4f7ffffe, v2
	v_cvt_u32_f32_e32 v2, v2
	s_max_i32 s1, s2, s1
	s_ashr_i32 s2, s4, 31
	v_readfirstlane_b32 s4, v2
	s_mul_i32 s3, s3, s4
	s_mul_hi_u32 s3, s4, s3
	s_add_i32 s4, s4, s3
	s_mul_hi_u32 s3, s1, s4
	s_mul_i32 s4, s3, s0
	s_sub_i32 s1, s1, s4
	s_add_i32 s5, s3, 1
	s_sub_i32 s4, s1, s0
	s_cmp_ge_u32 s1, s0
	s_cselect_b32 s3, s5, s3
	s_cselect_b32 s1, s4, s1
	s_add_i32 s4, s3, 1
	s_cmp_ge_u32 s1, s0
	s_cselect_b32 s0, s4, s3
	s_xor_b32 s0, s0, s2
	s_sub_i32 s20, s0, s2
	s_cmp_lt_i32 s20, 1
	v_readfirstlane_b32 s4, v0
	s_cbranch_scc1 .LBB0_1362
	s_mov_b64 s[0:1], 0
	s_cmpk_gt_i32 s6, 0x3ff
	s_mov_b64 s[2:3], 0
	s_cbranch_scc1 .LBB0_1363
	v_readlane_b32 s3, v243, 0
	s_ashr_i32 s2, s3, 31
	s_lshr_b32 s2, s2, 29
	s_add_i32 s5, s3, s2
	s_and_b32 s2, s5, -8
	s_sub_i32 s6, s3, s2
	s_cmp_gt_i32 s6, -1
	s_cbranch_scc0 .LBB0_1367
	s_lshl_b32 s7, s6, 7
	s_cbranch_execz .LBB0_1368
	s_branch .LBB0_1369

.LBB0_1699:
	v_readlane_b32 s2, v243, 51
	s_cmp_lt_i32 s2, 21
	s_cselect_b64 s[4:5], -1, 0
	s_and_b64 s[0:1], s[4:5], s[0:1]
	s_andn2_b64 vcc, exec, s[0:1]
	v_readlane_b32 s3, v243, 52
	s_cbranch_vccnz .LBB0_1745
	v_readlane_b32 s98, v243, 0
	s_lshr_b32 s98, s98, 0
	s_and_b32 s98, s98, 3
	s_mul_i32 s98, s98, 2

.Ldly_ph19_done:
	v_readlane_b32 s6, v243, 53
	s_abs_i32 s0, s6
	v_cvt_f32_u32_e32 v2, s0
	v_readlane_b32 s8, v243, 0
	s_sub_i32 s1, s6, s8
	s_add_i32 s2, s1, 0x3ff
	v_rcp_iflag_f32_e32 v2, v2
	s_sub_i32 s1, 0xfffffc01, s1
	s_xor_b32 s6, s2, s6
	s_sub_i32 s3, 0, s0
	v_mul_f32_e32 v2, 0x4f7ffffe, v2
	v_cvt_u32_f32_e32 v2, v2
	s_max_i32 s1, s2, s1
	s_ashr_i32 s2, s6, 31
	v_readfirstlane_b32 s10, v0
	v_readfirstlane_b32 s6, v2
	s_mul_i32 s3, s3, s6
	s_mul_hi_u32 s3, s6, s3
	s_add_i32 s6, s6, s3
	s_mul_hi_u32 s3, s1, s6
	s_mul_i32 s6, s3, s0
	s_sub_i32 s1, s1, s6
	s_add_i32 s7, s3, 1
	s_sub_i32 s6, s1, s0
	s_cmp_ge_u32 s1, s0
	s_cselect_b32 s3, s7, s3
	s_cselect_b32 s1, s6, s1
	s_add_i32 s6, s3, 1
	s_cmp_ge_u32 s1, s0
	s_cselect_b32 s0, s6, s3
	s_xor_b32 s0, s0, s2
	s_sub_i32 s20, s0, s2
	s_cmp_lt_i32 s20, 1
	s_cbranch_scc1 .LBB0_1704
	s_mov_b64 s[0:1], 0
	s_cmpk_gt_i32 s8, 0x3ff
	s_mov_b64 s[2:3], 0
	s_cbranch_scc1 .LBB0_1705
	v_readlane_b32 s3, v243, 0
	s_ashr_i32 s2, s3, 31
	s_lshr_b32 s2, s2, 29
	s_add_i32 s6, s3, s2
	s_and_b32 s2, s6, -8
	s_sub_i32 s7, s3, s2
	s_cmp_gt_i32 s7, -1
	s_cbranch_scc0 .LBB0_1709
	s_lshl_b32 s8, s7, 7
	s_cbranch_execz .LBB0_1710
	s_branch .LBB0_1711

.LBB0_2576:
	v_readlane_b32 s2, v243, 51
	s_cmp_lt_i32 s2, 31
	s_cselect_b64 s[4:5], -1, 0
	s_and_b64 s[0:1], s[4:5], s[0:1]
	s_andn2_b64 vcc, exec, s[0:1]
	v_readlane_b32 s3, v243, 52
	s_cbranch_vccnz .LBB0_2601
	v_readlane_b32 s98, v243, 0
	s_lshr_b32 s98, s98, 0
	s_and_b32 s98, s98, 3
	s_mul_i32 s98, s98, 2

.Ldly_ph28_done:
	v_readlane_b32 s0, v243, 0
	s_cmpk_gt_i32 s0, 0x3ff
	v_readfirstlane_b32 s3, v0
	s_cbranch_scc1 .LBB0_2601
	v_readlane_b32 s1, v243, 0
	s_ashr_i32 s20, s1, 31
	s_lshr_b32 s0, s20, 29
	s_add_i32 s6, s1, s0
	s_and_b32 s0, s6, -8
	s_sub_i32 s7, s1, s0
	s_cmp_gt_i32 s7, -1
	s_cbranch_scc0 .LBB0_2580
	s_lshl_b32 s2, s7, 7
	s_cbranch_execz .LBB0_2581
	s_branch .LBB0_2582

.LBB0_2784:
	v_readlane_b32 s2, v243, 51
	s_cmp_lt_i32 s2, 34
	s_cselect_b64 s[4:5], -1, 0
	s_and_b64 s[0:1], s[4:5], s[0:1]
	s_andn2_b64 vcc, exec, s[0:1]
	v_readlane_b32 s3, v243, 52
	s_cbranch_vccnz .LBB0_2830
	v_readlane_b32 s98, v243, 0
	s_lshr_b32 s98, s98, 0
	s_and_b32 s98, s98, 3
	s_mul_i32 s98, s98, 2

.Ldly_ph31_done:
	v_readlane_b32 s6, v243, 53
	s_abs_i32 s0, s6
	v_cvt_f32_u32_e32 v1, s0
	v_readlane_b32 s8, v243, 0
	s_sub_i32 s1, s6, s8
	s_add_i32 s2, s1, 0x3ff
	v_rcp_iflag_f32_e32 v1, v1
	s_sub_i32 s1, 0xfffffc01, s1
	s_xor_b32 s6, s2, s6
	s_sub_i32 s3, 0, s0
	v_mul_f32_e32 v1, 0x4f7ffffe, v1
	v_cvt_u32_f32_e32 v1, v1
	s_max_i32 s1, s2, s1
	s_ashr_i32 s2, s6, 31
	v_readfirstlane_b32 s10, v0
	v_readfirstlane_b32 s6, v1
	s_mul_i32 s3, s3, s6
	s_mul_hi_u32 s3, s6, s3
	s_add_i32 s6, s6, s3
	s_mul_hi_u32 s3, s1, s6
	s_mul_i32 s6, s3, s0
	s_sub_i32 s1, s1, s6
	s_add_i32 s7, s3, 1
	s_sub_i32 s6, s1, s0
	s_cmp_ge_u32 s1, s0
	s_cselect_b32 s3, s7, s3
	s_cselect_b32 s1, s6, s1
	s_add_i32 s6, s3, 1
	s_cmp_ge_u32 s1, s0
	s_cselect_b32 s0, s6, s3
	s_xor_b32 s0, s0, s2
	s_sub_i32 s20, s0, s2
	s_cmp_lt_i32 s20, 1
	s_cbranch_scc1 .LBB0_2789
	s_mov_b64 s[0:1], 0
	s_cmpk_gt_i32 s8, 0x3ff
	s_mov_b64 s[2:3], 0
	s_cbranch_scc1 .LBB0_2790
	v_readlane_b32 s3, v243, 0
	s_ashr_i32 s2, s3, 31
	s_lshr_b32 s2, s2, 29
	s_add_i32 s8, s3, s2
	s_and_b32 s2, s8, -8
	s_sub_i32 s6, s3, s2
	s_cmp_gt_i32 s6, -1
	s_cbranch_scc0 .LBB0_2794
	s_lshl_b32 s7, s6, 7
	s_ashr_i32 s2, s8, 3
	s_cbranch_execz .LBB0_2795
	s_branch .LBB0_2796

	.amdhsa_kernel _Z3fwd4Args
		.amdhsa_group_segment_fixed_size 0
		.amdhsa_private_segment_fixed_size 0
		.amdhsa_kernarg_size 520
		.amdhsa_user_sgpr_count 2
		.amdhsa_user_sgpr_dispatch_ptr 0
		.amdhsa_user_sgpr_queue_ptr 0
		.amdhsa_user_sgpr_kernarg_segment_ptr 1
		.amdhsa_user_sgpr_dispatch_id 0
		.amdhsa_user_sgpr_kernarg_preload_length 0
		.amdhsa_user_sgpr_kernarg_preload_offset 0
		.amdhsa_user_sgpr_private_segment_size 0
		.amdhsa_uses_dynamic_stack 0
		.amdhsa_enable_private_segment 0
		.amdhsa_system_sgpr_workgroup_id_x 1
		.amdhsa_system_sgpr_workgroup_id_y 0
		.amdhsa_system_sgpr_workgroup_id_z 0
		.amdhsa_system_sgpr_workgroup_info 0
		.amdhsa_system_vgpr_workitem_id 0
		.amdhsa_next_free_vgpr 256
		.amdhsa_next_free_sgpr 100
		.amdhsa_accum_offset 256
		.amdhsa_reserve_vcc 1
		.amdhsa_float_round_mode_32 0
		.amdhsa_float_round_mode_16_64 0
		.amdhsa_float_denorm_mode_32 3
		.amdhsa_float_denorm_mode_16_64 3
		.amdhsa_dx10_clamp 1
		.amdhsa_ieee_mode 1
		.amdhsa_fp16_overflow 0
		.amdhsa_tg_split 0
		.amdhsa_exception_fp_ieee_invalid_op 0
		.amdhsa_exception_fp_denorm_src 0
		.amdhsa_exception_fp_ieee_div_zero 0
		.amdhsa_exception_fp_ieee_overflow 0
		.amdhsa_exception_fp_ieee_underflow 0
		.amdhsa_exception_fp_ieee_inexact 0
		.amdhsa_exception_int_div_zero 0
	.end_amdhsa_kernel

amdhsa.kernels:
  - .agpr_count:     0
    .args:
      - .offset:         0
        .size:           264
        .value_kind:     by_value
      - .offset:         264
        .size:           4
        .value_kind:     hidden_block_count_x
      - .offset:         268
        .size:           4
        .value_kind:     hidden_block_count_y
      - .offset:         272
        .size:           4
        .value_kind:     hidden_block_count_z
      - .offset:         276
        .size:           2
        .value_kind:     hidden_group_size_x
      - .offset:         278
        .size:           2
        .value_kind:     hidden_group_size_y
      - .offset:         280
        .size:           2
        .value_kind:     hidden_group_size_z
      - .offset:         282
        .size:           2
        .value_kind:     hidden_remainder_x
      - .offset:         284
        .size:           2
        .value_kind:     hidden_remainder_y
      - .offset:         286
        .size:           2
        .value_kind:     hidden_remainder_z
      - .offset:         304
        .size:           8
        .value_kind:     hidden_global_offset_x
      - .offset:         312
        .size:           8
        .value_kind:     hidden_global_offset_y
      - .offset:         320
        .size:           8
        .value_kind:     hidden_global_offset_z
      - .offset:         328
        .size:           2
        .value_kind:     hidden_grid_dims
      - .offset:         384
        .size:           4
        .value_kind:     hidden_dynamic_lds_size
    .group_segment_fixed_size: 0
    .kernarg_segment_align: 8
    .kernarg_segment_size: 520
    .language:       OpenCL C
    .language_version:
      - 2
      - 0
    .max_flat_workgroup_size: 512
    .name:           _Z3fwd4Args
    .private_segment_fixed_size: 0
    .sgpr_count:     106
    .sgpr_spill_count: 122
    .symbol:         _Z3fwd4Args.kd
    .uniform_work_group_size: 1
    .uses_dynamic_stack: false
    .vgpr_count:     256
    .vgpr_spill_count: 0
    .wavefront_size: 64
